# GVTF fragment loads in mixer-A epilogue with nt
# speedup vs baseline: 1.0359x; 1.0359x over previous
.LBB0_327:
	s_lshl_b32 s72, s94, 1
	s_ashr_i32 s11, s10, 31
	s_ashr_i32 s73, s72, 31
	s_lshl_b64 s[16:17], s[72:73], 18
	s_lshl_b64 s[10:11], s[10:11], 15
	v_or_b32_e32 v228, s87, v236
	s_lshl_b32 s94, s94, 8
	s_or_b64 s[40:41], s[10:11], s[14:15]
	v_lshl_add_u64 v[136:137], v[216:217], 0, s[16:17]
	v_ashrrev_i32_e32 v229, 31, v228
	s_ashr_i32 s95, s94, 31
	v_lshl_add_u64 v[152:153], v[136:137], 0, s[40:41]
	s_waitcnt lgkmcnt(0)
	v_lshl_add_u64 v[116:117], v[228:229], 2, s[58:59]
	v_lshl_add_u64 v[154:155], s[94:95], 2, v[214:215]
	v_add_co_u32_e32 v136, vcc, 0x1000, v152
	global_load_dwordx4 v[112:115], v[116:117], off offset:16
	s_nop 0
	global_load_dwordx4 v[116:119], v[116:117], off
	s_nop 0
	global_load_dwordx4 v[192:195], v[154:155], off offset:16
	global_load_dwordx4 v[196:199], v[154:155], off
	v_addc_co_u32_e32 v137, vcc, 0, v153, vcc
	global_load_dwordx4 v[184:187], v[154:155], off offset:144
	global_load_dwordx4 v[188:191], v[154:155], off offset:128
	global_load_dwordx4 v[164:167], v[152:153], off nt
	global_load_dwordx4 v[148:151], v[152:153], off offset:1024 nt
	global_load_dwordx4 v[160:163], v[136:137], off nt
	global_load_dwordx4 v[144:147], v[136:137], off offset:1024 nt
	s_and_b64 vcc, exec, s[8:9]
	v_mov_b32_e32 v168, 0
	s_cbranch_vccnz .LBB0_330
	v_add_co_u32_e32 v136, vcc, 0x1000, v152
	global_load_dwordx4 v[172:175], v[154:155], off offset:256
	global_load_dwordx4 v[180:183], v[154:155], off offset:272
	v_addc_co_u32_e32 v137, vcc, 0, v153, vcc
	global_load_dwordx4 v[140:143], v[152:153], off offset:2048 nt
	s_nop 0
	global_load_dwordx4 v[136:139], v[136:137], off offset:2048 nt
	s_and_b64 vcc, exec, s[8:9]
	s_cbranch_vccz .LBB0_331

.LBB0_331:
	global_load_dwordx4 v[168:171], v[154:155], off offset:384
	global_load_dwordx4 v[176:179], v[154:155], off offset:400
	v_add_co_u32_e32 v154, vcc, 0x1000, v152
	s_nop 1
	v_addc_co_u32_e32 v155, vcc, 0, v153, vcc
	global_load_dwordx4 v[156:159], v[152:153], off offset:3072 nt
	s_nop 0
	global_load_dwordx4 v[152:155], v[154:155], off offset:3072 nt

.LBB0_350:
	global_load_dword v77, v[168:169], off offset:192
	v_lshlrev_b32_e32 v78, 16, v75
	v_and_b32_e32 v75, 0xffff0000, v75
	v_add_u32_e32 v76, s94, v242
	s_or_b32 s16, s72, 1
	s_ashr_i32 s17, s16, 31
	s_lshl_b32 s26, s16, 7
	s_lshl_b64 s[16:17], s[16:17], 18
	s_ashr_i32 s27, s26, 31
	v_lshl_add_u64 v[88:89], s[26:27], 2, v[214:215]
	v_mov_b32_e32 v96, 0
	s_waitcnt vmcnt(0)
	v_fma_f32 v68, v116, v68, v77
	v_fma_f32 v69, v117, v69, v77
	v_mul_f32_e32 v68, v68, v78
	v_mul_f32_e32 v69, v69, v75
	v_cvt_pk_bf16_f32 v68, v68, v69
	v_lshlrev_b32_e32 v69, 16, v74
	v_fma_f32 v70, v118, v70, v77
	v_mul_f32_e32 v69, v70, v69
	v_and_b32_e32 v70, 0xffff0000, v74
	v_fma_f32 v71, v119, v71, v77
	v_mul_f32_e32 v70, v71, v70
	v_cvt_pk_bf16_f32 v69, v69, v70
	v_lshlrev_b32_e32 v70, 16, v73
	v_fma_f32 v64, v112, v64, v77
	v_mul_f32_e32 v64, v64, v70
	v_and_b32_e32 v70, 0xffff0000, v73
	v_fma_f32 v65, v113, v65, v77
	v_mul_f32_e32 v65, v65, v70
	v_cvt_pk_bf16_f32 v70, v64, v65
	v_lshlrev_b32_e32 v64, 16, v72
	v_fma_f32 v65, v114, v66, v77
	v_mul_f32_e32 v64, v65, v64
	v_and_b32_e32 v65, 0xffff0000, v72
	v_fmac_f32_e32 v77, v115, v67
	v_mul_f32_e32 v65, v77, v65
	v_ashrrev_i32_e32 v77, 31, v76
	v_cvt_pk_bf16_f32 v71, v64, v65
	v_lshlrev_b64 v[64:65], 12, v[76:77]
	v_lshl_add_u64 v[64:65], s[12:13], 0, v[64:65]
	v_lshl_add_u64 v[64:65], v[228:229], 1, v[64:65]
	global_store_dwordx4 v[64:65], v[68:71], off
	v_lshl_add_u64 v[64:65], v[216:217], 0, s[16:17]
	v_lshl_add_u64 v[90:91], v[64:65], 0, s[40:41]
	v_add_co_u32_e32 v72, vcc, 0x1000, v90
	global_load_dwordx4 v[100:103], v[88:89], off offset:16
	global_load_dwordx4 v[104:107], v[88:89], off
	v_addc_co_u32_e32 v73, vcc, 0, v91, vcc
	global_load_dwordx4 v[64:67], v[90:91], off nt
	global_load_dwordx4 v[68:71], v[72:73], off nt
	global_load_dwordx4 v[128:131], v[88:89], off offset:144
	global_load_dwordx4 v[132:135], v[88:89], off offset:128
	global_load_dwordx4 v[80:83], v[90:91], off offset:1024 nt
	global_load_dwordx4 v[84:87], v[72:73], off offset:1024 nt
	s_and_b64 vcc, exec, s[8:9]
	s_cbranch_vccnz .LBB0_355
	v_add_co_u32_e32 v72, vcc, 0x1000, v90
	global_load_dwordx4 v[108:111], v[88:89], off offset:256
	global_load_dwordx4 v[124:127], v[88:89], off offset:272
	v_addc_co_u32_e32 v73, vcc, 0, v91, vcc
	global_load_dwordx4 v[76:79], v[90:91], off offset:2048 nt
	s_nop 0
	global_load_dwordx4 v[72:75], v[72:73], off offset:2048 nt
	s_and_b64 vcc, exec, s[8:9]
	s_cbranch_vccz .LBB0_356

.LBB0_356:
	global_load_dwordx4 v[96:99], v[88:89], off offset:384
	global_load_dwordx4 v[120:123], v[88:89], off offset:400
	v_add_co_u32_e32 v88, vcc, 0x1000, v90
	s_nop 1
	v_addc_co_u32_e32 v89, vcc, 0, v91, vcc
	global_load_dwordx4 v[92:95], v[90:91], off offset:3072 nt
	s_nop 0
	global_load_dwordx4 v[88:91], v[88:89], off offset:3072 nt
